# first merge pass K-loop: counted lgkmcnt waits at the loop top (MFMAs start as fragments land) and redundant LDS wait before the second MFMA group removed
# speedup vs baseline: 1.0004x; 1.0004x over previous
.LBB0_1009:
	s_mul_hi_u32 s28, s52, 0xaaaaaaab
	s_lshr_b32 s28, s28, 1
	s_mul_i32 s28, s28, 3
	s_sub_i32 s34, s52, s28
	s_add_i32 s28, s52, 2
	s_cmp_ge_i32 s28, s61
	s_mul_i32 s34, s34, 0xc000
	s_cselect_b64 s[28:29], -1, 0
	s_add_i32 s34, s34, 0
	s_waitcnt lgkmcnt(7)
	v_mfma_f32_16x16x32_bf16 v[142:145], v[18:21], v[2:5], v[142:145]
	v_add_u32_e32 v146, s34, v173
	v_add_u32_e32 v147, s34, v174
	ds_read_b128 v[154:157], v146 offset:16384
	ds_read_b128 v[150:153], v146 offset:18432
	ds_read_b128 v[158:161], v147 offset:16384
	ds_read_b128 v[146:149], v147 offset:18432
	s_waitcnt lgkmcnt(10)
	v_mfma_f32_16x16x32_bf16 v[138:141], v[22:25], v[2:5], v[138:141]
	s_or_b64 s[28:29], s[30:31], s[28:29]
	s_and_b64 vcc, exec, s[28:29]
	s_mov_b64 s[28:29], -1
	s_waitcnt lgkmcnt(7)
	v_mfma_f32_16x16x32_bf16 v[134:137], v[34:37], v[2:5], v[134:137]
	s_waitcnt lgkmcnt(6)
	v_mfma_f32_16x16x32_bf16 v[130:133], v[38:41], v[2:5], v[130:133]
	v_mfma_f32_16x16x32_bf16 v[126:129], v[18:21], v[6:9], v[126:129]
	v_mfma_f32_16x16x32_bf16 v[122:125], v[22:25], v[6:9], v[122:125]
	v_mfma_f32_16x16x32_bf16 v[118:121], v[34:37], v[6:9], v[118:121]
	v_mfma_f32_16x16x32_bf16 v[114:117], v[38:41], v[6:9], v[114:117]
	v_mfma_f32_16x16x32_bf16 v[142:145], v[26:29], v[10:13], v[142:145]
	v_mfma_f32_16x16x32_bf16 v[138:141], v[30:33], v[10:13], v[138:141]
	s_waitcnt lgkmcnt(5)
	v_mfma_f32_16x16x32_bf16 v[134:137], v[42:45], v[10:13], v[134:137]
	s_waitcnt lgkmcnt(4)
	v_mfma_f32_16x16x32_bf16 v[130:133], v[46:49], v[10:13], v[130:133]
	v_mfma_f32_16x16x32_bf16 v[126:129], v[26:29], v[14:17], v[126:129]
	v_mfma_f32_16x16x32_bf16 v[122:125], v[30:33], v[14:17], v[122:125]
	v_mfma_f32_16x16x32_bf16 v[118:121], v[42:45], v[14:17], v[118:121]
	v_mfma_f32_16x16x32_bf16 v[114:117], v[46:49], v[14:17], v[114:117]
	s_cbranch_vccnz .LBB0_1011
	s_waitcnt vmcnt(6)
	s_mov_b64 s[28:29], 0

.LBB0_1066:
	v_mfma_f32_16x16x32_bf16 v[110:113], v[18:21], v[154:157], v[110:113]
	s_andn2_b64 vcc, exec, s[28:29]
	v_mfma_f32_16x16x32_bf16 v[106:109], v[22:25], v[154:157], v[106:109]
	v_mfma_f32_16x16x32_bf16 v[102:105], v[34:37], v[154:157], v[102:105]
	v_mfma_f32_16x16x32_bf16 v[98:101], v[38:41], v[154:157], v[98:101]
	v_mfma_f32_16x16x32_bf16 v[94:97], v[18:21], v[150:153], v[94:97]
	v_mfma_f32_16x16x32_bf16 v[90:93], v[22:25], v[150:153], v[90:93]
	v_mfma_f32_16x16x32_bf16 v[86:89], v[34:37], v[150:153], v[86:89]
	v_mfma_f32_16x16x32_bf16 v[82:85], v[38:41], v[150:153], v[82:85]
	v_mfma_f32_16x16x32_bf16 v[110:113], v[26:29], v[158:161], v[110:113]
	v_mfma_f32_16x16x32_bf16 v[106:109], v[30:33], v[158:161], v[106:109]
	v_mfma_f32_16x16x32_bf16 v[102:105], v[42:45], v[158:161], v[102:105]
	v_mfma_f32_16x16x32_bf16 v[98:101], v[46:49], v[158:161], v[98:101]
	v_mfma_f32_16x16x32_bf16 v[94:97], v[26:29], v[146:149], v[94:97]
	v_mfma_f32_16x16x32_bf16 v[90:93], v[30:33], v[146:149], v[90:93]
	v_mfma_f32_16x16x32_bf16 v[86:89], v[42:45], v[146:149], v[86:89]
	v_mfma_f32_16x16x32_bf16 v[82:85], v[46:49], v[146:149], v[82:85]
	s_cbranch_vccnz .LBB0_1068
	s_add_i32 s28, s30, 0
	v_add_u32_e32 v38, s28, v175
	v_add_u32_e32 v46, s28, v176
	ds_read_b128 v[18:21], v38 offset:32768
	ds_read_b128 v[22:25], v38 offset:34816
	ds_read_b128 v[26:29], v46 offset:32768
	ds_read_b128 v[30:33], v46 offset:34816
	ds_read_b128 v[34:37], v38 offset:36864
	ds_read_b128 v[38:41], v38 offset:38912
	ds_read_b128 v[42:45], v46 offset:36864
	ds_read_b128 v[46:49], v46 offset:38912
